# NA mask/bias: 16 serialized exec-masked LDS reads per score half replaced by batched reads plus v_cndmask (4 instances), on top of the GQA loop rewrite
# speedup vs baseline: 1.0017x; 1.0017x over previous
; __device__ __forceinline__ int v_rd_base(int lane) { return ((lane & 3) << 3) | (((lane >> 2) & 3) << 6) | (((lane >> 4) & 1) << 5) | (((lane >> 5) & 1) << 8); }
; __device__ __forceinline__ void na_mask(f32x16& p0, f32x16& p1, int kr, int r0, int qrow, int qc, int c0, int hi, const float* bl) {
;   const bool tv = (kr >= r0) && (kr < r0 + 8);
;   if (!tv) {
; #pragma unroll
;     for (int r = 0; r < 16; ++r) { p0[r] = -1e30f; p1[r] = -1e30f; }
; template <bool NA, int ROWB>
; __device__ __forceinline__ void attn_dma(const bf16* __restrict__ Qb, const bf16* __restrict__ Kh, const bf16* __restrict__ Vh, bf16* __restrict__ Ob, int NT, char* lds, const int tid, float* __restrict__ ssb, int qrow0, int kr_lo, const float* bl) {
;   const int wid = tid >> 6, lane = tid & 63, r32 = lane & 31, hi = lane >> 5;
;   const int wid_s = __builtin_amdgcn_readfirstlane(wid);
;   char* V_lds = lds; char* K_lds = lds + 3 * SHM_V;
;   float* li_l = (float*)(lds + 3 * SHM_V + 3 * SHM_K) + wid * 64;
;   float* al_l = li_l + 32;
;   float m_reg = -1e30f, l_reg = 0; f32x16 o[4] = {}; bf16x8 qr[8];
;   const int qrow = qrow0 + (wid >> 1), qc = 32 * (wid & 1) + r32;
;   const int c0 = min(max(qc - 8, 0), 48), r0 = min(max(qrow - 4, 0), 120);
;   const bf16* Qw = Qb + (long)(wid * QBLK + r32) * LDQ + hi * 8;
; #pragma unroll
;   for (int d0 = 0; d0 < 8; ++d0) qr[d0] = *reinterpret_cast<const bf16x8*>(Qw + d0 * 16);
;   const int vb0 = (int)(uintptr_t)V_lds + v_rd_base(lane);
;   auto src_off = [&](int i, unsigned& ko, unsigned& vo) __attribute__((always_inline)) {
;     const int b = (wid * 2 + i) * 1024 + lane * 16;
;     { const int row = b >> 8, cb = (b & 255) ^ ((row & 7) << 4); ko = (unsigned)(row * ROWB + cb); }
;     { const int st = b >> 9, within = b & 511, kk = (st >> 2) * 8 + (within >> 6), c = (st & 3) * 32 + ((within & 63) >> 1);
;       const int k = (kk & ~0xC) | ((kk & 4) << 1) | ((kk & 8) >> 1); vo = (unsigned)(k * ROWB + c * 2); }
;   };
;   unsigned ksrc[2], vsrc[2];
;   if constexpr (!NA) { src_off(0, ksrc[0], vsrc[0]); src_off(1, ksrc[1], vsrc[1]); }
;     ...
;   f32x16 pA0, pA1, pB0, pB1; bf16x8 pa0, pa1, pa2, pa3; float mnA, mnB, alA, alB;
;   DMA_TILE(0, 0); DMA_TILE(1, 1); VM0(); __syncthreads();
;   qkt<false>(pA0, pA1, (const bf16*)K_lds, qr, nullptr, r32, hi); NAM(pA0, pA1, 0); PSM(pA0, pA1, mnA, alA);
.LBB0_145:
	s_or_b64 exec, exec, s[18:19]
	s_ashr_i32 s0, s25, 3
	s_waitcnt lgkmcnt(0)
	s_lshl_b32 s22, s0, 8
	s_mov_b32 s18, s22
	s_lshl_b32 s14, s0, 2
	v_writelane_b32 v254, s18, 51
	s_max_i32 s37, s14, 4
	s_add_i32 s16, s37, -4
	v_writelane_b32 v254, s19, 52
	s_mul_i32 s1, s0, 0x240000
	v_readlane_b32 s38, v254, 47
	s_mul_hi_i32 s15, s22, 0x2400
	v_readlane_b32 s39, v254, 48
	s_add_u32 s1, s38, s1
	s_addc_u32 s15, s39, s15
	s_lshl_b32 s22, s36, 8
	s_add_u32 s18, s1, s22
	s_addc_u32 s19, s15, 0
	v_lshl_add_u64 v[0:1], s[18:19], 0, v[130:131]
	v_lshl_add_u64 v[0:1], v[0:1], 0, v[112:113]
	global_load_dwordx4 v[100:103], v[0:1], off
	global_load_dwordx4 v[126:129], v[0:1], off offset:32
	global_load_dwordx4 v[122:125], v[0:1], off offset:64
	global_load_dwordx4 v[118:121], v[0:1], off offset:96
	global_load_dwordx4 v[114:117], v[0:1], off offset:128
	global_load_dwordx4 v[108:111], v[0:1], off offset:160
	global_load_dwordx4 v[104:107], v[0:1], off offset:192
	global_load_dwordx4 v[96:99], v[0:1], off offset:224
	s_mul_i32 s1, s16, 0x90000
	s_lshl_b32 s17, s16, 6
	s_mul_hi_u32 s17, s17, 0x2400
	s_add_u32 s18, s38, s1
	s_addc_u32 s19, s39, s17
	s_add_u32 s18, s18, s22
	s_addc_u32 s19, s19, 0
	v_readfirstlane_b32 s15, v168
	s_add_u32 s22, s18, 0x1000
	s_addc_u32 s23, s19, 0
	s_lshl_b32 s33, s15, 11
	v_lshl_add_u64 v[0:1], s[18:19], 0, v[132:133]
	s_add_i32 s38, s33, 0
	v_lshl_add_u64 v[0:1], v[0:1], 0, s[28:29]
	s_add_i32 m0, s38, 0xc000
	v_lshl_add_u64 v[2:3], s[18:19], 0, v[136:137]
	v_lshl_add_u64 v[4:5], s[22:23], 0, v[134:135]
	global_load_lds_dwordx4 v[0:1], off
	s_mov_b32 m0, s38
	v_lshl_add_u64 v[2:3], v[2:3], 0, s[28:29]
	global_load_lds_dwordx4 v[4:5], off
	s_add_i32 m0, s38, 0xc400
	v_lshl_add_u64 v[6:7], s[22:23], 0, v[138:139]
	global_load_lds_dwordx4 v[2:3], off
	s_add_i32 m0, s38, 0x400
	s_add_u32 s22, s18, 0x90800
	s_addc_u32 s23, s19, 0
	s_add_u32 s18, s18, 0x91000
	global_load_lds_dwordx4 v[6:7], off
	v_lshl_add_u64 v[0:1], s[22:23], 0, v[132:133]
	s_addc_u32 s19, s19, 0
	s_add_i32 m0, s38, 0x10000
	v_lshl_add_u64 v[2:3], s[22:23], 0, v[136:137]
	global_load_lds_dwordx4 v[0:1], off
	v_lshl_add_u64 v[0:1], s[18:19], 0, v[134:135]
	s_add_i32 m0, s38, 0x4000
	v_lshl_add_u64 v[4:5], s[18:19], 0, v[138:139]
	global_load_lds_dwordx4 v[0:1], off
	s_add_i32 m0, s38, 0x10400
	v_add_u32_e32 v8, 0, v173
	global_load_lds_dwordx4 v[2:3], off
	s_add_i32 m0, s38, 0x4400
	v_add_u32_e32 v36, 0, v174
	global_load_lds_dwordx4 v[4:5], off
	s_waitcnt vmcnt(0)
	s_waitcnt vmcnt(0) lgkmcnt(0)
	s_barrier
	ds_read_b128 v[0:3], v8 offset:49152
	ds_read_b128 v[32:35], v36 offset:49152
	v_add_u32_e32 v189, s14, v170
	s_waitcnt lgkmcnt(1)
	v_mfma_f32_32x32x16_bf16 v[16:31], v[0:3], v[100:103], 0
	ds_read_b128 v[0:3], v8 offset:57344
	s_waitcnt lgkmcnt(1)
	v_mfma_f32_32x32x16_bf16 v[16:31], v[32:35], v[126:129], v[16:31]
	ds_read_b128 v[32:35], v36 offset:57344
	v_add_u32_e32 v36, 0, v175
	s_waitcnt lgkmcnt(1)
	v_mfma_f32_32x32x16_bf16 v[0:15], v[0:3], v[100:103], 0
	s_waitcnt lgkmcnt(0)
	v_mfma_f32_32x32x16_bf16 v[0:15], v[32:35], v[126:129], v[0:15]
	ds_read_b128 v[32:35], v36 offset:49152
	s_waitcnt lgkmcnt(0)
	v_mfma_f32_32x32x16_bf16 v[16:31], v[32:35], v[122:125], v[16:31]
	ds_read_b128 v[32:35], v36 offset:57344
	v_add_u32_e32 v36, 0, v176
	s_waitcnt lgkmcnt(0)
	v_mfma_f32_32x32x16_bf16 v[0:15], v[32:35], v[122:125], v[0:15]
	ds_read_b128 v[32:35], v36 offset:49152
	s_waitcnt lgkmcnt(0)
	v_mfma_f32_32x32x16_bf16 v[16:31], v[32:35], v[118:121], v[16:31]
	ds_read_b128 v[32:35], v36 offset:57344
	v_add_u32_e32 v36, 0, v177
	s_waitcnt lgkmcnt(0)
	v_mfma_f32_32x32x16_bf16 v[0:15], v[32:35], v[118:121], v[0:15]
	ds_read_b128 v[32:35], v36 offset:49152
	s_waitcnt lgkmcnt(0)
	v_mfma_f32_32x32x16_bf16 v[16:31], v[32:35], v[114:117], v[16:31]
	ds_read_b128 v[32:35], v36 offset:57344
	v_add_u32_e32 v36, 0, v178
	s_waitcnt lgkmcnt(0)
	v_mfma_f32_32x32x16_bf16 v[0:15], v[32:35], v[114:117], v[0:15]
	ds_read_b128 v[32:35], v36 offset:49152
	s_waitcnt lgkmcnt(0)
	v_mfma_f32_32x32x16_bf16 v[16:31], v[32:35], v[108:111], v[16:31]
	ds_read_b128 v[32:35], v36 offset:57344
	v_add_u32_e32 v36, 0, v179
	s_waitcnt lgkmcnt(0)
	v_mfma_f32_32x32x16_bf16 v[0:15], v[32:35], v[108:111], v[0:15]
	ds_read_b128 v[32:35], v36 offset:49152
	s_waitcnt lgkmcnt(0)
	v_mfma_f32_32x32x16_bf16 v[16:31], v[32:35], v[104:107], v[16:31]
	ds_read_b128 v[32:35], v36 offset:57344
	v_add_u32_e32 v36, 0, v180
	s_waitcnt lgkmcnt(0)
	v_mfma_f32_32x32x16_bf16 v[0:15], v[32:35], v[104:107], v[0:15]
	ds_read_b128 v[32:35], v36 offset:49152
	s_waitcnt lgkmcnt(0)
	v_mfma_f32_32x32x16_bf16 v[16:31], v[32:35], v[96:99], v[16:31]
	ds_read_b128 v[32:35], v36 offset:57344
	v_max_i32_e32 v36, 4, v189
	v_add_u32_e32 v36, -4, v36
	v_min_u32_e32 v190, 0x78, v36
	v_add_u32_e32 v191, 8, v190
	v_cmp_lt_u32_e32 vcc, s16, v190
	v_cmp_ge_u32_e64 s[18:19], s16, v191
	s_waitcnt lgkmcnt(0)
	v_mfma_f32_32x32x16_bf16 v[0:15], v[32:35], v[96:99], v[0:15]
	s_or_b64 s[14:15], vcc, s[18:19]
	s_and_saveexec_b64 s[18:19], s[14:15]
	s_xor_b64 s[14:15], exec, s[18:19]
	s_or_saveexec_b64 s[18:19], s[14:15]
	v_mov_b32_e32 v36, 0xf149f2ca
	v_mov_b32_e32 v35, 0xf149f2ca
	v_mov_b32_e32 v34, 0xf149f2ca
	v_mov_b32_e32 v33, 0xf149f2ca
	v_mov_b32_e32 v32, 0xf149f2ca
	v_mov_b32_e32 v39, 0xf149f2ca
	v_mov_b32_e32 v38, 0xf149f2ca
	v_mov_b32_e32 v41, 0xf149f2ca
	v_mov_b32_e32 v40, 0xf149f2ca
	v_mov_b32_e32 v43, 0xf149f2ca
	v_mov_b32_e32 v42, 0xf149f2ca
	v_mov_b32_e32 v45, 0xf149f2ca
	v_mov_b32_e32 v44, 0xf149f2ca
	v_mov_b32_e32 v47, 0xf149f2ca
	v_mov_b32_e32 v46, 0xf149f2ca
	v_mov_b32_e32 v62, 0xf149f2ca
	v_mov_b32_e32 v63, 0xf149f2ca
	v_mov_b32_e32 v60, 0xf149f2ca
	v_mov_b32_e32 v61, 0xf149f2ca
	v_mov_b32_e32 v58, 0xf149f2ca
	v_mov_b32_e32 v59, 0xf149f2ca
	v_mov_b32_e32 v56, 0xf149f2ca
	v_mov_b32_e32 v57, 0xf149f2ca
	v_mov_b32_e32 v54, 0xf149f2ca
	v_mov_b32_e32 v55, 0xf149f2ca
	v_mov_b32_e32 v52, 0xf149f2ca
	v_mov_b32_e32 v53, 0xf149f2ca
	v_mov_b32_e32 v50, 0xf149f2ca
	v_mov_b32_e32 v51, 0xf149f2ca
	v_mov_b32_e32 v48, 0xf149f2ca
	v_mov_b32_e32 v49, 0xf149f2ca
	v_mov_b32_e32 v37, 0xf149f2ca
	s_xor_b64 exec, exec, s[18:19]
	s_cbranch_execz .LBB0_181
; __device__ __forceinline__ void na_mask(f32x16& p0, f32x16& p1, int kr, int r0, int qrow, int qc, int c0, int hi, const float* bl) {
;     ...
;   } else {
;     const float* brow = bl + (kr - qrow + 7) * 31 + 15 - qc + 4 * hi;
;     const int d = 4 * hi - c0;
; #pragma unroll
;     for (int r = 0; r < 16; ++r) {
;       const int kc = (r & 3) + 8 * (r >> 2);
;       const float b0 = brow[kc], b1 = brow[kc + 32];
;       p0[r] = (unsigned)(d + kc) < 16u ? p0[r] + b0 : -1e30f; p1[r] = (unsigned)(d + kc + 32) < 16u ? p1[r] + b1 : -1e30f;
;     }
;   }
	v_sub_u32_e32 v32, s16, v189
	s_movk_i32 s14, 0x7c
	v_mul_lo_u32 v32, v32, s14
	v_add_u32_e32 v33, v184, v32
	ds_read_b32 v32, v33 offset:188
	v_mov_b32_e32 v48, 0xf149f2ca
	v_mov_b32_e32 v49, 0xf149f2ca
	v_mov_b32_e32 v50, 0xf149f2ca
	v_mov_b32_e32 v51, 0xf149f2ca
	v_mov_b32_e32 v52, 0xf149f2ca
	v_mov_b32_e32 v53, 0xf149f2ca
	v_mov_b32_e32 v54, 0xf149f2ca
	v_mov_b32_e32 v55, 0xf149f2ca
	v_mov_b32_e32 v56, 0xf149f2ca
	v_mov_b32_e32 v57, 0xf149f2ca
	v_mov_b32_e32 v58, 0xf149f2ca
	v_mov_b32_e32 v59, 0xf149f2ca
	v_mov_b32_e32 v60, 0xf149f2ca
	v_mov_b32_e32 v61, 0xf149f2ca
	v_mov_b32_e32 v62, 0xf149f2ca
	v_mov_b32_e32 v63, 0xf149f2ca
	ds_read_b32 v49, v33 offset:60
	ds_read_b32 v48, v33 offset:64
	ds_read_b32 v51, v33 offset:68
	ds_read_b32 v50, v33 offset:72
	ds_read_b32 v53, v33 offset:92
	ds_read_b32 v52, v33 offset:96
	ds_read_b32 v55, v33 offset:100
	ds_read_b32 v54, v33 offset:104
	ds_read_b32 v57, v33 offset:124
	ds_read_b32 v56, v33 offset:128
	ds_read_b32 v59, v33 offset:132
	ds_read_b32 v58, v33 offset:136
	ds_read_b32 v61, v33 offset:156
	ds_read_b32 v60, v33 offset:160
	ds_read_b32 v63, v33 offset:164
	ds_read_b32 v62, v33 offset:168
	s_waitcnt lgkmcnt(0)
	v_add_f32_e32 v49, v16, v49
	v_add_f32_e32 v48, v17, v48
	v_add_f32_e32 v51, v18, v51
	v_add_f32_e32 v50, v19, v50
	v_add_f32_e32 v53, v20, v53
	v_add_f32_e32 v52, v21, v52
	v_add_f32_e32 v55, v22, v55
	v_add_f32_e32 v54, v23, v54
	v_add_f32_e32 v57, v24, v57
	v_add_f32_e32 v56, v25, v56
	v_add_f32_e32 v59, v26, v59
	v_add_f32_e32 v58, v27, v58
	v_add_f32_e32 v61, v28, v61
	v_add_f32_e32 v60, v29, v60
	v_add_f32_e32 v63, v30, v63
	v_add_f32_e32 v62, v31, v62
	ds_read_b32 v16, v33 offset:192
	ds_read_b32 v17, v33 offset:196
	ds_read_b32 v18, v33 offset:200
	ds_read_b32 v19, v33 offset:220
	ds_read_b32 v20, v33 offset:224
	ds_read_b32 v21, v33 offset:228
	ds_read_b32 v22, v33 offset:232
	ds_read_b32 v23, v33 offset:252
	ds_read_b32 v24, v33 offset:256
	ds_read_b32 v25, v33 offset:260
	ds_read_b32 v26, v33 offset:264
	ds_read_b32 v27, v33 offset:284
	ds_read_b32 v28, v33 offset:288
	ds_read_b32 v29, v33 offset:292
	ds_read_b32 v30, v33 offset:296
	v_cndmask_b32_e64 v49, v239, v49, s[42:43]
	v_cndmask_b32_e64 v48, v239, v48, s[46:47]
	v_cndmask_b32_e64 v51, v239, v51, s[50:51]
	v_cndmask_b32_e64 v50, v239, v50, s[54:55]
	v_cndmask_b32_e64 v53, v239, v53, s[58:59]
	v_cndmask_b32_e64 v52, v239, v52, s[62:63]
	v_cndmask_b32_e64 v55, v239, v55, s[66:67]
	v_cndmask_b32_e64 v54, v239, v54, s[70:71]
	v_cndmask_b32_e64 v57, v239, v57, s[74:75]
	v_cndmask_b32_e64 v56, v239, v56, s[78:79]
	v_cndmask_b32_e64 v59, v239, v59, s[82:83]
	v_cndmask_b32_e64 v58, v239, v58, s[86:87]
	v_cndmask_b32_e64 v61, v239, v61, s[90:91]
	v_cndmask_b32_e64 v60, v239, v60, s[94:95]
	v_cndmask_b32_e64 v63, v239, v63, s[4:5]
	v_cndmask_b32_e64 v62, v239, v62, s[8:9]
	s_waitcnt lgkmcnt(14)
	v_add_f32_e32 v0, v0, v32
	v_cndmask_b32_e64 v46, v239, v0, s[44:45]
	v_add_f32_e32 v0, v1, v16
	v_cndmask_b32_e64 v47, v239, v0, s[48:49]
	s_waitcnt lgkmcnt(13)
	v_add_f32_e32 v0, v2, v17
	v_cndmask_b32_e64 v44, v239, v0, s[52:53]
	s_waitcnt lgkmcnt(12)
	v_add_f32_e32 v0, v3, v18
	v_cndmask_b32_e64 v45, v239, v0, s[56:57]
	s_waitcnt lgkmcnt(11)
	v_add_f32_e32 v0, v4, v19
	v_cndmask_b32_e64 v42, v239, v0, s[60:61]
	s_waitcnt lgkmcnt(10)
	v_add_f32_e32 v0, v5, v20
	v_cndmask_b32_e64 v43, v239, v0, s[64:65]
	s_waitcnt lgkmcnt(9)
	v_add_f32_e32 v0, v6, v21
	v_cndmask_b32_e64 v40, v239, v0, s[68:69]
	s_waitcnt lgkmcnt(8)
	v_add_f32_e32 v0, v7, v22
	v_cndmask_b32_e64 v41, v239, v0, s[72:73]
	s_waitcnt lgkmcnt(7)
	v_add_f32_e32 v0, v8, v23
	v_cndmask_b32_e64 v38, v239, v0, s[76:77]
	s_waitcnt lgkmcnt(6)
	v_add_f32_e32 v0, v9, v24
	v_cndmask_b32_e64 v39, v239, v0, s[80:81]
	s_waitcnt lgkmcnt(5)
	v_add_f32_e32 v0, v10, v25
	v_cndmask_b32_e64 v32, v239, v0, s[84:85]
	s_waitcnt lgkmcnt(4)
	v_add_f32_e32 v0, v11, v26
	v_cndmask_b32_e64 v33, v239, v0, s[88:89]
	s_waitcnt lgkmcnt(3)
	v_add_f32_e32 v0, v12, v27
	v_cndmask_b32_e64 v34, v239, v0, s[92:93]
	s_waitcnt lgkmcnt(2)
	v_add_f32_e32 v0, v13, v28
	v_cndmask_b32_e64 v35, v239, v0, s[96:97]
	s_waitcnt lgkmcnt(1)
	v_add_f32_e32 v0, v14, v29
	v_cndmask_b32_e64 v36, v239, v0, s[6:7]
	s_waitcnt lgkmcnt(0)
	v_add_f32_e32 v0, v15, v30
	v_cndmask_b32_e64 v37, v239, v0, s[10:11]

; #define SBAR() __builtin_amdgcn_sched_barrier(0)
; #define NAM(P0, P1, t) do { if constexpr (NA) na_mask(P0, P1, kr_lo + (t), r0, qrow, qc, c0, hi, bl); } while (0)
; #define NAM(P0, P1, t) do { if constexpr (NA) na_mask(P0, P1, kr_lo + (t), r0, qrow, qc, c0, hi, bl); } while (0)
; __device__ __forceinline__ void na_mask(f32x16& p0, f32x16& p1, int kr, int r0, int qrow, int qc, int c0, int hi, const float* bl) {
;   const bool tv = (kr >= r0) && (kr < r0 + 8);
;   if (!tv) {
; #pragma unroll
;     for (int r = 0; r < 16; ++r) { p0[r] = -1e30f; p1[r] = -1e30f; }
; template <bool NA, int ROWB>
; __device__ __forceinline__ void attn_dma(const bf16* __restrict__ Qb, const bf16* __restrict__ Kh, const bf16* __restrict__ Vh, bf16* __restrict__ Ob, int NT, char* lds, const int tid, float* __restrict__ ssb, int qrow0, int kr_lo, const float* bl) {
;     ...
;   for (int t = 1; t + 1 < NT; t += 2) {
;     DMA_TILE(t + 1, bn);
;     SBAR(); qkt<false>(pB0, pB1, (const bf16*)(K_lds + bc * SHM_K), qr, nullptr, r32, hi); NAM(pB0, pB1, t);
.LBB0_182:
	s_lshl_b32 s39, s17, 14
	s_add_i32 s1, s39, 0
	v_lshl_add_u64 v[160:161], s[28:29], 0, v[132:133]
	s_mov_b64 s[18:19], 0x1f520800
	s_add_i32 s14, s1, s33
	v_lshl_add_u64 v[64:65], v[160:161], 0, s[18:19]
	s_add_i32 m0, s14, 0xc000
	v_lshl_add_u64 v[162:163], s[28:29], 0, v[134:135]
	s_mov_b64 vcc, 0x1f521000
	global_load_lds_dwordx4 v[64:65], off
	v_lshl_add_u64 v[64:65], v[162:163], 0, vcc
	s_mov_b32 m0, s14
	v_lshl_add_u64 v[164:165], s[28:29], 0, v[136:137]
	global_load_lds_dwordx4 v[64:65], off
	v_lshl_add_u64 v[64:65], v[164:165], 0, s[18:19]
	s_add_i32 m0, s14, 0xc400
	v_lshl_add_u64 v[166:167], s[28:29], 0, v[142:143]
	global_load_lds_dwordx4 v[64:65], off
	v_lshl_add_u64 v[64:65], v[166:167], 0, vcc
	s_add_i32 m0, s14, 0x400
	s_nop 0
	global_load_lds_dwordx4 v[64:65], off
	s_lshl_b32 s30, s0, 14
	s_add_i32 s0, s30, 0
	v_add_u32_e32 v68, s0, v173
	ds_read_b128 v[64:67], v68 offset:49152
	ds_read_b128 v[68:71], v68 offset:57344
	v_add_u32_e32 v195, s0, v174
	ds_read_b128 v[196:199], v195 offset:49152
	ds_read_b128 v[222:225], v195 offset:57344
	v_add_u32_e32 v195, s0, v175
	s_waitcnt lgkmcnt(0)
	v_mfma_f32_32x32x16_bf16 v[80:95], v[64:67], v[100:103], 0
	s_add_i32 s22, s37, s27
	v_mov_b32_e32 v241, 0xf149f2ca
	v_mov_b32_e32 v242, 0xf149f2ca
	v_mov_b32_e32 v243, 0xf149f2ca
	v_mov_b32_e32 v246, 0xf149f2ca
	v_mov_b32_e32 v247, 0xf149f2ca
	v_mov_b32_e32 v248, 0xf149f2ca
	v_mfma_f32_32x32x16_bf16 v[64:79], v[68:71], v[100:103], 0
	v_mov_b32_e32 v249, 0xf149f2ca
	v_mov_b32_e32 v250, 0xf149f2ca
	v_mov_b32_e32 v251, 0xf149f2ca
	v_mov_b32_e32 v237, 0xf149f2ca
	v_mov_b32_e32 v235, 0xf149f2ca
	v_mov_b32_e32 v203, 0xf149f2ca
	v_mov_b32_e32 v244, 0xf149f2ca
	v_mfma_f32_32x32x16_bf16 v[80:95], v[196:199], v[126:129], v[80:95]
	v_mov_b32_e32 v245, 0xf149f2ca
	v_mov_b32_e32 v238, 0xf149f2ca
	v_mov_b32_e32 v240, 0xf149f2ca
	v_mov_b32_e32 v234, 0xf149f2ca
	v_mov_b32_e32 v236, 0xf149f2ca
	v_mov_b32_e32 v230, 0xf149f2ca
	v_mov_b32_e32 v232, 0xf149f2ca
	v_mfma_f32_32x32x16_bf16 v[64:79], v[222:225], v[126:129], v[64:79]
	ds_read_b128 v[196:199], v195 offset:49152
	ds_read_b128 v[222:225], v195 offset:57344
	v_add_u32_e32 v195, s0, v176
	v_mov_b32_e32 v228, 0xf149f2ca
	v_mov_b32_e32 v229, 0xf149f2ca
	v_mov_b32_e32 v226, 0xf149f2ca
	v_mov_b32_e32 v221, 0xf149f2ca
	s_waitcnt lgkmcnt(0)
	v_mfma_f32_32x32x16_bf16 v[80:95], v[196:199], v[122:125], v[80:95]
	v_mfma_f32_32x32x16_bf16 v[64:79], v[222:225], v[122:125], v[64:79]
	ds_read_b128 v[196:199], v195 offset:49152
	ds_read_b128 v[222:225], v195 offset:57344
	v_add_u32_e32 v195, s0, v177
	s_waitcnt lgkmcnt(0)
	v_mfma_f32_32x32x16_bf16 v[80:95], v[196:199], v[118:121], v[80:95]
	v_mfma_f32_32x32x16_bf16 v[64:79], v[222:225], v[118:121], v[64:79]
	ds_read_b128 v[196:199], v195 offset:49152
	ds_read_b128 v[222:225], v195 offset:57344
	v_add_u32_e32 v195, s0, v178
	s_waitcnt lgkmcnt(0)
	v_mfma_f32_32x32x16_bf16 v[80:95], v[196:199], v[114:117], v[80:95]
	v_mfma_f32_32x32x16_bf16 v[64:79], v[222:225], v[114:117], v[64:79]
	ds_read_b128 v[196:199], v195 offset:49152
	ds_read_b128 v[222:225], v195 offset:57344
	v_add_u32_e32 v195, s0, v179
	s_waitcnt lgkmcnt(0)
	v_mfma_f32_32x32x16_bf16 v[80:95], v[196:199], v[108:111], v[80:95]
	v_mfma_f32_32x32x16_bf16 v[64:79], v[222:225], v[108:111], v[64:79]
	ds_read_b128 v[196:199], v195 offset:49152
	ds_read_b128 v[222:225], v195 offset:57344
	v_add_u32_e32 v195, s0, v180
	s_add_i32 s0, s22, -6
	v_cmp_ge_u32_e32 vcc, s0, v190
	v_cmp_lt_u32_e64 s[18:19], s0, v191
	s_and_b64 s[14:15], vcc, s[18:19]
	s_waitcnt lgkmcnt(0)
	v_mfma_f32_32x32x16_bf16 v[80:95], v[196:199], v[104:107], v[80:95]
	v_mfma_f32_32x32x16_bf16 v[64:79], v[222:225], v[104:107], v[64:79]
	ds_read_b128 v[196:199], v195 offset:49152
	ds_read_b128 v[222:225], v195 offset:57344
	s_waitcnt lgkmcnt(0)
	v_mfma_f32_32x32x16_bf16 v[80:95], v[196:199], v[96:99], v[80:95]
	v_mov_b32_e32 v196, 0xf149f2ca
	v_mov_b32_e32 v197, 0xf149f2ca
	v_mov_b32_e32 v198, 0xf149f2ca
	v_mov_b32_e32 v199, 0xf149f2ca
	v_mfma_f32_32x32x16_bf16 v[64:79], v[222:225], v[96:99], v[64:79]
	v_mov_b32_e32 v225, 0xf149f2ca
	v_mov_b32_e32 v223, 0xf149f2ca
	v_mov_b32_e32 v224, 0xf149f2ca
	v_mov_b32_e32 v222, 0xf149f2ca
	s_and_saveexec_b64 s[18:19], s[14:15]
	s_cbranch_execz .LBB0_216
; __device__ __forceinline__ void na_mask(f32x16& p0, f32x16& p1, int kr, int r0, int qrow, int qc, int c0, int hi, const float* bl) {
;     ...
;   } else {
;     const float* brow = bl + (kr - qrow + 7) * 31 + 15 - qc + 4 * hi;
;     const int d = 4 * hi - c0;
; #pragma unroll
;     for (int r = 0; r < 16; ++r) {
;       const int kc = (r & 3) + 8 * (r >> 2);
;       const float b0 = brow[kc], b1 = brow[kc + 32];
;       p0[r] = (unsigned)(d + kc) < 16u ? p0[r] + b0 : -1e30f; p1[r] = (unsigned)(d + kc + 32) < 16u ? p1[r] + b1 : -1e30f;
;     }
;   }
	ds_read_b32 v195, v193 offset:128
	v_mov_b32_e32 v221, 0xf149f2ca
	v_mov_b32_e32 v222, 0xf149f2ca
	v_mov_b32_e32 v223, 0xf149f2ca
	v_mov_b32_e32 v224, 0xf149f2ca
	v_mov_b32_e32 v225, 0xf149f2ca
	v_mov_b32_e32 v226, 0xf149f2ca
	v_mov_b32_e32 v228, 0xf149f2ca
	v_mov_b32_e32 v229, 0xf149f2ca
	v_mov_b32_e32 v230, 0xf149f2ca
	v_mov_b32_e32 v232, 0xf149f2ca
	v_mov_b32_e32 v234, 0xf149f2ca
	v_mov_b32_e32 v236, 0xf149f2ca
	v_mov_b32_e32 v238, 0xf149f2ca
	v_mov_b32_e32 v240, 0xf149f2ca
	v_mov_b32_e32 v244, 0xf149f2ca
	v_mov_b32_e32 v245, 0xf149f2ca
	ds_read_b32 v222, v193
	ds_read_b32 v221, v193 offset:4
	ds_read_b32 v224, v193 offset:8
	ds_read_b32 v223, v193 offset:12
	ds_read_b32 v226, v193 offset:32
	ds_read_b32 v225, v193 offset:36
	ds_read_b32 v229, v193 offset:40
	ds_read_b32 v228, v193 offset:44
	ds_read_b32 v232, v193 offset:64
	ds_read_b32 v230, v193 offset:68
	ds_read_b32 v236, v193 offset:72
	ds_read_b32 v234, v193 offset:76
	ds_read_b32 v240, v193 offset:96
	ds_read_b32 v238, v193 offset:100
	ds_read_b32 v245, v193 offset:104
	ds_read_b32 v244, v193 offset:108
	s_waitcnt lgkmcnt(0)
	v_add_f32_e32 v222, v80, v222
	v_add_f32_e32 v221, v81, v221
	v_add_f32_e32 v224, v82, v224
	v_add_f32_e32 v223, v83, v223
	v_add_f32_e32 v226, v84, v226
	v_add_f32_e32 v225, v85, v225
	v_add_f32_e32 v229, v86, v229
	v_add_f32_e32 v228, v87, v228
	v_add_f32_e32 v232, v88, v232
	v_add_f32_e32 v230, v89, v230
	v_add_f32_e32 v236, v90, v236
	v_add_f32_e32 v234, v91, v234
	v_add_f32_e32 v240, v92, v240
	v_add_f32_e32 v238, v93, v238
	v_add_f32_e32 v245, v94, v245
	v_add_f32_e32 v244, v95, v244
	ds_read_b32 v80, v193 offset:132
	ds_read_b32 v81, v193 offset:136
	ds_read_b32 v82, v193 offset:140
	ds_read_b32 v83, v193 offset:160
	ds_read_b32 v84, v193 offset:164
	ds_read_b32 v85, v193 offset:168
	ds_read_b32 v86, v193 offset:172
	ds_read_b32 v87, v193 offset:192
	ds_read_b32 v88, v193 offset:196
	ds_read_b32 v89, v193 offset:200
	ds_read_b32 v90, v193 offset:204
	ds_read_b32 v91, v193 offset:224
	ds_read_b32 v92, v193 offset:228
	ds_read_b32 v196, v193 offset:232
	ds_read_b32 v93, v193 offset:236
	v_cndmask_b32_e64 v222, v239, v222, s[42:43]
	v_cndmask_b32_e64 v221, v239, v221, s[46:47]
	v_cndmask_b32_e64 v224, v239, v224, s[50:51]
	v_cndmask_b32_e64 v223, v239, v223, s[54:55]
	v_cndmask_b32_e64 v226, v239, v226, s[58:59]
	v_cndmask_b32_e64 v225, v239, v225, s[62:63]
	v_cndmask_b32_e64 v229, v239, v229, s[66:67]
	v_cndmask_b32_e64 v228, v239, v228, s[70:71]
	v_cndmask_b32_e64 v232, v239, v232, s[74:75]
	v_cndmask_b32_e64 v230, v239, v230, s[78:79]
	v_cndmask_b32_e64 v236, v239, v236, s[82:83]
	v_cndmask_b32_e64 v234, v239, v234, s[86:87]
	v_cndmask_b32_e64 v240, v239, v240, s[90:91]
	v_cndmask_b32_e64 v238, v239, v238, s[94:95]
	v_cndmask_b32_e64 v245, v239, v245, s[4:5]
	v_cndmask_b32_e64 v244, v239, v244, s[8:9]
	s_waitcnt lgkmcnt(0)
	v_add_f32_e32 v64, v64, v195
	v_add_f32_e32 v78, v78, v196
	v_add_f32_e32 v77, v77, v92
	v_add_f32_e32 v76, v76, v91
	v_add_f32_e32 v75, v75, v90
	v_add_f32_e32 v74, v74, v89
	v_add_f32_e32 v73, v73, v88
	v_add_f32_e32 v72, v72, v87
	v_add_f32_e32 v71, v71, v86
	v_add_f32_e32 v70, v70, v85
	v_add_f32_e32 v69, v69, v84
	v_add_f32_e32 v68, v68, v83
	v_add_f32_e32 v67, v67, v82
	v_add_f32_e32 v66, v66, v81
	v_add_f32_e32 v65, v65, v80
	v_cndmask_b32_e64 v198, v239, v64, s[44:45]
	v_add_f32_e32 v64, v79, v93
	v_cndmask_b32_e64 v241, v239, v78, s[6:7]
	v_cndmask_b32_e64 v242, v239, v77, s[96:97]
	v_cndmask_b32_e64 v243, v239, v76, s[92:93]
	v_cndmask_b32_e64 v246, v239, v75, s[88:89]
	v_cndmask_b32_e64 v247, v239, v74, s[84:85]
	v_cndmask_b32_e64 v248, v239, v73, s[80:81]
	v_cndmask_b32_e64 v249, v239, v72, s[76:77]
	v_cndmask_b32_e64 v250, v239, v71, s[72:73]
	v_cndmask_b32_e64 v251, v239, v70, s[68:69]
	v_cndmask_b32_e64 v237, v239, v69, s[64:65]
	v_cndmask_b32_e64 v235, v239, v68, s[60:61]
	v_cndmask_b32_e64 v203, v239, v67, s[56:57]
	v_cndmask_b32_e64 v196, v239, v66, s[52:53]
	v_cndmask_b32_e64 v197, v239, v65, s[48:49]
	v_cndmask_b32_e64 v199, v239, v64, s[10:11]

; #define SBAR() __builtin_amdgcn_sched_barrier(0)
; #define NAM(P0, P1, t) do { if constexpr (NA) na_mask(P0, P1, kr_lo + (t), r0, qrow, qc, c0, hi, bl); } while (0)
; #define NAM(P0, P1, t) do { if constexpr (NA) na_mask(P0, P1, kr_lo + (t), r0, qrow, qc, c0, hi, bl); } while (0)
; __device__ __forceinline__ void na_mask(f32x16& p0, f32x16& p1, int kr, int r0, int qrow, int qc, int c0, int hi, const float* bl) {
;   const bool tv = (kr >= r0) && (kr < r0 + 8);
;   if (!tv) {
; #pragma unroll
;     for (int r = 0; r < 16; ++r) { p0[r] = -1e30f; p1[r] = -1e30f; }
; template <bool NA, int ROWB>
; __device__ __forceinline__ void attn_dma(const bf16* __restrict__ Qb, const bf16* __restrict__ Kh, const bf16* __restrict__ Vh, bf16* __restrict__ Ob, int NT, char* lds, const int tid, float* __restrict__ ssb, int qrow0, int kr_lo, const float* bl) {
;     ...
;     if (t + 2 < NT) DMA_TILE(t + 2, bn);
;     SBAR(); qkt<false>(pA0, pA1, (const bf16*)(K_lds + bc * SHM_K), qr, nullptr, r32, hi); NAM(pA0, pA1, t + 1);
.LBB0_222:
	v_add_u32_e32 v68, s1, v173
	ds_read_b128 v[64:67], v68 offset:49152
	v_add_u32_e32 v148, s1, v174
	ds_read_b128 v[144:147], v148 offset:49152
	s_waitcnt lgkmcnt(0)
	v_mfma_f32_32x32x16_bf16 v[80:95], v[64:67], v[100:103], 0
	ds_read_b128 v[64:67], v68 offset:57344
	v_mfma_f32_32x32x16_bf16 v[80:95], v[144:147], v[126:129], v[80:95]
	ds_read_b128 v[144:147], v148 offset:57344
	v_add_u32_e32 v148, s1, v175
	s_waitcnt lgkmcnt(0)
	v_mfma_f32_32x32x16_bf16 v[64:79], v[64:67], v[100:103], 0
	v_mfma_f32_32x32x16_bf16 v[64:79], v[144:147], v[126:129], v[64:79]
	ds_read_b128 v[144:147], v148 offset:49152
	s_waitcnt lgkmcnt(0)
	v_mfma_f32_32x32x16_bf16 v[80:95], v[144:147], v[122:125], v[80:95]
	ds_read_b128 v[144:147], v148 offset:57344
	v_add_u32_e32 v148, s1, v176
	s_waitcnt lgkmcnt(0)
	v_mfma_f32_32x32x16_bf16 v[64:79], v[144:147], v[122:125], v[64:79]
	ds_read_b128 v[144:147], v148 offset:49152
	s_waitcnt lgkmcnt(0)
	v_mfma_f32_32x32x16_bf16 v[80:95], v[144:147], v[118:121], v[80:95]
	ds_read_b128 v[144:147], v148 offset:57344
	v_add_u32_e32 v148, s1, v177
	s_waitcnt lgkmcnt(0)
	v_mfma_f32_32x32x16_bf16 v[64:79], v[144:147], v[118:121], v[64:79]
	ds_read_b128 v[144:147], v148 offset:49152
	s_waitcnt lgkmcnt(0)
	v_mfma_f32_32x32x16_bf16 v[80:95], v[144:147], v[114:117], v[80:95]
	ds_read_b128 v[144:147], v148 offset:57344
	v_add_u32_e32 v148, s1, v178
	s_waitcnt lgkmcnt(0)
	v_mfma_f32_32x32x16_bf16 v[64:79], v[144:147], v[114:117], v[64:79]
	ds_read_b128 v[144:147], v148 offset:49152
	s_waitcnt lgkmcnt(0)
	v_mfma_f32_32x32x16_bf16 v[80:95], v[144:147], v[108:111], v[80:95]
	ds_read_b128 v[144:147], v148 offset:57344
	v_add_u32_e32 v148, s1, v179
	s_waitcnt lgkmcnt(0)
	v_mfma_f32_32x32x16_bf16 v[64:79], v[144:147], v[108:111], v[64:79]
	ds_read_b128 v[144:147], v148 offset:49152
	s_waitcnt lgkmcnt(0)
	v_mfma_f32_32x32x16_bf16 v[80:95], v[144:147], v[104:107], v[80:95]
	ds_read_b128 v[144:147], v148 offset:57344
	v_add_u32_e32 v148, s1, v180
	s_add_i32 s1, s22, -5
	v_cmp_lt_u32_e64 s[22:23], s1, v190
	v_cmp_ge_u32_e32 vcc, s1, v191
	s_or_b64 s[14:15], s[22:23], vcc
	s_waitcnt lgkmcnt(0)
	v_mfma_f32_32x32x16_bf16 v[64:79], v[144:147], v[104:107], v[64:79]
	ds_read_b128 v[144:147], v148 offset:49152
	s_waitcnt lgkmcnt(0)
	v_mfma_f32_32x32x16_bf16 v[80:95], v[144:147], v[96:99], v[80:95]
	ds_read_b128 v[144:147], v148 offset:57344
	s_waitcnt lgkmcnt(0)
	v_mfma_f32_32x32x16_bf16 v[64:79], v[144:147], v[96:99], v[64:79]
	s_and_saveexec_b64 s[22:23], s[14:15]
	s_xor_b64 s[14:15], exec, s[22:23]
	s_or_saveexec_b64 s[22:23], s[14:15]
	v_mov_b32_e32 v158, 0xf149f2ca
	v_mov_b32_e32 v157, 0xf149f2ca
	v_mov_b32_e32 v156, 0xf149f2ca
	v_mov_b32_e32 v155, 0xf149f2ca
	v_mov_b32_e32 v154, 0xf149f2ca
	v_mov_b32_e32 v153, 0xf149f2ca
	v_mov_b32_e32 v152, 0xf149f2ca
	v_mov_b32_e32 v151, 0xf149f2ca
	v_mov_b32_e32 v150, 0xf149f2ca
	v_mov_b32_e32 v149, 0xf149f2ca
	v_mov_b32_e32 v148, 0xf149f2ca
	v_mov_b32_e32 v147, 0xf149f2ca
	v_mov_b32_e32 v146, 0xf149f2ca
	v_mov_b32_e32 v145, 0xf149f2ca
	v_mov_b32_e32 v144, 0xf149f2ca
	v_mov_b32_e32 v212, 0xf149f2ca
	v_mov_b32_e32 v213, 0xf149f2ca
	v_mov_b32_e32 v210, 0xf149f2ca
	v_mov_b32_e32 v211, 0xf149f2ca
	v_mov_b32_e32 v208, 0xf149f2ca
	v_mov_b32_e32 v209, 0xf149f2ca
	v_mov_b32_e32 v206, 0xf149f2ca
	v_mov_b32_e32 v207, 0xf149f2ca
	v_mov_b32_e32 v167, 0xf149f2ca
	v_mov_b32_e32 v205, 0xf149f2ca
	v_mov_b32_e32 v165, 0xf149f2ca
	v_mov_b32_e32 v166, 0xf149f2ca
	v_mov_b32_e32 v163, 0xf149f2ca
	v_mov_b32_e32 v164, 0xf149f2ca
	v_mov_b32_e32 v161, 0xf149f2ca
	v_mov_b32_e32 v162, 0xf149f2ca
	v_mov_b32_e32 v159, 0xf149f2ca
	s_xor_b64 exec, exec, s[22:23]
	s_cbranch_execz .LBB0_258
; __device__ __forceinline__ void na_mask(f32x16& p0, f32x16& p1, int kr, int r0, int qrow, int qc, int c0, int hi, const float* bl) {
;     ...
;   } else {
;     const float* brow = bl + (kr - qrow + 7) * 31 + 15 - qc + 4 * hi;
;     const int d = 4 * hi - c0;
; #pragma unroll
;     for (int r = 0; r < 16; ++r) {
;       const int kc = (r & 3) + 8 * (r >> 2);
;       const float b0 = brow[kc], b1 = brow[kc + 32];
;       p0[r] = (unsigned)(d + kc) < 16u ? p0[r] + b0 : -1e30f; p1[r] = (unsigned)(d + kc + 32) < 16u ? p1[r] + b1 : -1e30f;
;     }
;   }
	ds_read_b32 v144, v193 offset:252
	v_mov_b32_e32 v161, 0xf149f2ca
	v_mov_b32_e32 v162, 0xf149f2ca
	v_mov_b32_e32 v163, 0xf149f2ca
	v_mov_b32_e32 v164, 0xf149f2ca
	v_mov_b32_e32 v165, 0xf149f2ca
	v_mov_b32_e32 v166, 0xf149f2ca
	v_mov_b32_e32 v167, 0xf149f2ca
	v_mov_b32_e32 v205, 0xf149f2ca
	v_mov_b32_e32 v206, 0xf149f2ca
	v_mov_b32_e32 v207, 0xf149f2ca
	v_mov_b32_e32 v208, 0xf149f2ca
	v_mov_b32_e32 v209, 0xf149f2ca
	v_mov_b32_e32 v210, 0xf149f2ca
	v_mov_b32_e32 v211, 0xf149f2ca
	v_mov_b32_e32 v212, 0xf149f2ca
	v_mov_b32_e32 v213, 0xf149f2ca
	ds_read_b32 v162, v193 offset:124
	ds_read_b32 v161, v193 offset:128
	ds_read_b32 v164, v193 offset:132
	ds_read_b32 v163, v193 offset:136
	ds_read_b32 v166, v193 offset:156
	ds_read_b32 v165, v193 offset:160
	ds_read_b32 v205, v193 offset:164
	ds_read_b32 v167, v193 offset:168
	ds_read_b32 v207, v193 offset:188
	ds_read_b32 v206, v193 offset:192
	ds_read_b32 v209, v193 offset:196
	ds_read_b32 v208, v193 offset:200
	ds_read_b32 v211, v193 offset:220
	ds_read_b32 v210, v193 offset:224
	ds_read_b32 v213, v193 offset:228
	ds_read_b32 v212, v193 offset:232
	s_waitcnt lgkmcnt(0)
	v_add_f32_e32 v162, v80, v162
	v_add_f32_e32 v161, v81, v161
	v_add_f32_e32 v164, v82, v164
	v_add_f32_e32 v163, v83, v163
	v_add_f32_e32 v166, v84, v166
	v_add_f32_e32 v165, v85, v165
	v_add_f32_e32 v205, v86, v205
	v_add_f32_e32 v167, v87, v167
	v_add_f32_e32 v207, v88, v207
	v_add_f32_e32 v206, v89, v206
	v_add_f32_e32 v209, v90, v209
	v_add_f32_e32 v208, v91, v208
	v_add_f32_e32 v211, v92, v211
	v_add_f32_e32 v210, v93, v210
	v_add_f32_e32 v213, v94, v213
	v_add_f32_e32 v212, v95, v212
	ds_read_b32 v80, v193 offset:256
	ds_read_b32 v81, v193 offset:260
	ds_read_b32 v82, v193 offset:264
	ds_read_b32 v83, v193 offset:284
	ds_read_b32 v84, v193 offset:288
	ds_read_b32 v85, v193 offset:292
	ds_read_b32 v86, v193 offset:296
	ds_read_b32 v87, v193 offset:316
	ds_read_b32 v88, v193 offset:320
	ds_read_b32 v89, v193 offset:324
	ds_read_b32 v90, v193 offset:328
	ds_read_b32 v91, v193 offset:348
	ds_read_b32 v92, v193 offset:352
	ds_read_b32 v93, v193 offset:356
	ds_read_b32 v94, v193 offset:360
	v_cndmask_b32_e64 v162, v239, v162, s[42:43]
	v_cndmask_b32_e64 v161, v239, v161, s[46:47]
	v_cndmask_b32_e64 v164, v239, v164, s[50:51]
	v_cndmask_b32_e64 v163, v239, v163, s[54:55]
	v_cndmask_b32_e64 v166, v239, v166, s[58:59]
	v_cndmask_b32_e64 v165, v239, v165, s[62:63]
	v_cndmask_b32_e64 v205, v239, v205, s[66:67]
	v_cndmask_b32_e64 v167, v239, v167, s[70:71]
	v_cndmask_b32_e64 v207, v239, v207, s[74:75]
	v_cndmask_b32_e64 v206, v239, v206, s[78:79]
	v_cndmask_b32_e64 v209, v239, v209, s[82:83]
	v_cndmask_b32_e64 v208, v239, v208, s[86:87]
	v_cndmask_b32_e64 v211, v239, v211, s[90:91]
	v_cndmask_b32_e64 v210, v239, v210, s[94:95]
	v_cndmask_b32_e64 v213, v239, v213, s[4:5]
	v_cndmask_b32_e64 v212, v239, v212, s[8:9]
	s_waitcnt lgkmcnt(0)
	v_add_f32_e32 v64, v64, v144
	v_cndmask_b32_e64 v144, v239, v64, s[44:45]
	v_add_f32_e32 v64, v65, v80
	v_cndmask_b32_e64 v145, v239, v64, s[48:49]
	v_add_f32_e32 v64, v66, v81
	v_cndmask_b32_e64 v146, v239, v64, s[52:53]
	v_add_f32_e32 v64, v67, v82
	v_cndmask_b32_e64 v147, v239, v64, s[56:57]
	v_add_f32_e32 v64, v68, v83
	v_cndmask_b32_e64 v148, v239, v64, s[60:61]
	v_add_f32_e32 v64, v69, v84
	v_cndmask_b32_e64 v149, v239, v64, s[64:65]
	v_add_f32_e32 v64, v70, v85
	v_cndmask_b32_e64 v150, v239, v64, s[68:69]
	v_add_f32_e32 v64, v71, v86
	v_cndmask_b32_e64 v151, v239, v64, s[72:73]
	v_add_f32_e32 v64, v72, v87
	v_cndmask_b32_e64 v152, v239, v64, s[76:77]
	v_add_f32_e32 v64, v73, v88
	v_cndmask_b32_e64 v153, v239, v64, s[80:81]
	v_add_f32_e32 v64, v74, v89
	v_cndmask_b32_e64 v154, v239, v64, s[84:85]
	v_add_f32_e32 v64, v75, v90
	v_cndmask_b32_e64 v155, v239, v64, s[88:89]
	v_add_f32_e32 v64, v76, v91
	v_cndmask_b32_e64 v156, v239, v64, s[92:93]
	v_add_f32_e32 v64, v77, v92
	v_cndmask_b32_e64 v157, v239, v64, s[96:97]
	v_add_f32_e32 v64, v78, v93
	v_cndmask_b32_e64 v158, v239, v64, s[6:7]
	v_add_f32_e32 v64, v79, v94
	v_cndmask_b32_e64 v159, v239, v64, s[10:11]

; #define SBAR() __builtin_amdgcn_sched_barrier(0)
; #define NAM(P0, P1, t) do { if constexpr (NA) na_mask(P0, P1, kr_lo + (t), r0, qrow, qc, c0, hi, bl); } while (0)
; #define PSM(P0, P1, MN, AL) do { if constexpr (NA) partialSM(P0, P1, m_reg, MN, AL); else { AL = 1.f; _Pragma("unroll") for (int r = 0; r < 16; ++r) P0[r] = __builtin_amdgcn_exp2f(P0[r]); } } while (0)
; #define RESCN(a) do { if constexpr (NA) RESC(a); } while (0)
; #define NAM(P0, P1, t) do { if constexpr (NA) na_mask(P0, P1, kr_lo + (t), r0, qrow, qc, c0, hi, bl); } while (0)
; #define PSM(P0, P1, MN, AL) do { if constexpr (NA) partialSM(P0, P1, m_reg, MN, AL); else { AL = 1.f; _Pragma("unroll") for (int r = 0; r < 16; ++r) P0[r] = __builtin_amdgcn_exp2f(P0[r]); } } while (0)
; #define RESCN(a) do { if constexpr (NA) RESC(a); } while (0)
; __device__ __forceinline__ void na_mask(f32x16& p0, f32x16& p1, int kr, int r0, int qrow, int qc, int c0, int hi, const float* bl) {
;   const bool tv = (kr >= r0) && (kr < r0 + 8);
;   if (!tv) {
; #pragma unroll
;     for (int r = 0; r < 16; ++r) { p0[r] = -1e30f; p1[r] = -1e30f; }
; template <bool NA, int ROWB>
; __device__ __forceinline__ void attn_dma(const bf16* __restrict__ Qb, const bf16* __restrict__ Kh, const bf16* __restrict__ Vh, bf16* __restrict__ Ob, int NT, char* lds, const int tid, float* __restrict__ ssb, int qrow0, int kr_lo, const float* bl) {
;     ...
;   SBAR(); qkt<false>(pB0, pB1, (const bf16*)(K_lds + bc * SHM_K), qr, nullptr, r32, hi); NAM(pB0, pB1, NT - 1);
;   finishSM(pA0, pA1, alA, l_reg, pa0, pa1, pa2, pa3); SBAR();
;   pv_d0(o, vb0 + bp * (int)SHM_V, pa0, pa1, pa2, pa3); PSM(pB0, pB1, mnB, alB); RESCN(alB);
.LBB0_264:
	s_lshl_b32 s0, s0, 14
	s_add_i32 s1, s0, 0
	v_add_u32_e32 v68, s1, v173
	ds_read_b128 v[64:67], v68 offset:49152
	ds_read_b128 v[68:71], v68 offset:57344
	v_add_u32_e32 v161, s1, v174
	s_waitcnt lgkmcnt(1)
	v_mfma_f32_32x32x16_bf16 v[80:95], v[64:67], v[100:103], 0
	s_waitcnt lgkmcnt(0)
	v_mfma_f32_32x32x16_bf16 v[64:79], v[68:71], v[100:103], 0
	ds_read_b128 v[100:103], v161 offset:49152
	ds_read_b128 v[162:165], v161 offset:57344
	s_waitcnt lgkmcnt(1)
	v_mfma_f32_32x32x16_bf16 v[80:95], v[100:103], v[126:129], v[80:95]
	s_waitcnt lgkmcnt(0)
	v_mfma_f32_32x32x16_bf16 v[64:79], v[162:165], v[126:129], v[64:79]
	v_add_u32_e32 v126, s1, v175
	ds_read_b128 v[100:103], v126 offset:49152
	ds_read_b128 v[126:129], v126 offset:57344
	s_waitcnt lgkmcnt(1)
	v_mfma_f32_32x32x16_bf16 v[80:95], v[100:103], v[122:125], v[80:95]
	s_waitcnt lgkmcnt(0)
	v_mfma_f32_32x32x16_bf16 v[64:79], v[126:129], v[122:125], v[64:79]
	v_add_u32_e32 v122, s1, v176
	ds_read_b128 v[100:103], v122 offset:49152
	ds_read_b128 v[122:125], v122 offset:57344
	v_mov_b32_e32 v126, 0xf149f2ca
	v_mov_b32_e32 v127, 0xf149f2ca
	v_mov_b32_e32 v128, 0xf149f2ca
	v_mov_b32_e32 v129, 0xf149f2ca
	s_waitcnt lgkmcnt(1)
	v_mfma_f32_32x32x16_bf16 v[80:95], v[100:103], v[118:121], v[80:95]
	s_waitcnt lgkmcnt(0)
	v_mfma_f32_32x32x16_bf16 v[64:79], v[122:125], v[118:121], v[64:79]
	v_add_u32_e32 v118, s1, v177
	ds_read_b128 v[100:103], v118 offset:49152
	ds_read_b128 v[118:121], v118 offset:57344
	v_mov_b32_e32 v122, 0xf149f2ca
	v_mov_b32_e32 v123, 0xf149f2ca
	v_mov_b32_e32 v124, 0xf149f2ca
	v_mov_b32_e32 v125, 0xf149f2ca
	s_waitcnt lgkmcnt(1)
	v_mfma_f32_32x32x16_bf16 v[80:95], v[100:103], v[114:117], v[80:95]
	s_waitcnt lgkmcnt(0)
	v_mfma_f32_32x32x16_bf16 v[64:79], v[118:121], v[114:117], v[64:79]
	v_add_u32_e32 v114, s1, v178
	ds_read_b128 v[100:103], v114 offset:49152
	ds_read_b128 v[114:117], v114 offset:57344
	v_mov_b32_e32 v118, 0xf149f2ca
	v_mov_b32_e32 v119, 0xf149f2ca
	v_mov_b32_e32 v120, 0xf149f2ca
	v_mov_b32_e32 v121, 0xf149f2ca
	s_waitcnt lgkmcnt(1)
	v_mfma_f32_32x32x16_bf16 v[80:95], v[100:103], v[108:111], v[80:95]
	s_waitcnt lgkmcnt(0)
	v_mfma_f32_32x32x16_bf16 v[64:79], v[114:117], v[108:111], v[64:79]
	v_add_u32_e32 v108, s1, v179
	ds_read_b128 v[100:103], v108 offset:49152
	ds_read_b128 v[108:111], v108 offset:57344
	v_mov_b32_e32 v114, 0xf149f2ca
	v_mov_b32_e32 v117, 0xf149f2ca
	v_mov_b32_e32 v115, 0xf149f2ca
	v_mov_b32_e32 v116, 0xf149f2ca
	s_waitcnt lgkmcnt(1)
	v_mfma_f32_32x32x16_bf16 v[80:95], v[100:103], v[104:107], v[80:95]
	s_waitcnt lgkmcnt(0)
	v_mfma_f32_32x32x16_bf16 v[64:79], v[108:111], v[104:107], v[64:79]
	v_add_u32_e32 v104, s1, v180
	ds_read_b128 v[100:103], v104 offset:49152
	ds_read_b128 v[104:107], v104 offset:57344
	s_add_i32 s1, s37, s16
	s_add_i32 s1, s1, -5
	v_cmp_ge_i32_e32 vcc, s1, v190
	v_cmp_lt_i32_e64 s[18:19], s1, v191
	s_and_b64 s[14:15], vcc, s[18:19]
	s_waitcnt lgkmcnt(1)
	v_mfma_f32_32x32x16_bf16 v[80:95], v[100:103], v[96:99], v[80:95]
	v_mov_b32_e32 v110, 0xf149f2ca
	v_mov_b32_e32 v111, 0xf149f2ca
	v_mov_b32_e32 v108, 0xf149f2ca
	v_mov_b32_e32 v109, 0xf149f2ca
	v_mov_b32_e32 v102, 0xf149f2ca
	v_mov_b32_e32 v103, 0xf149f2ca
	v_mov_b32_e32 v100, 0xf149f2ca
	s_waitcnt lgkmcnt(0)
	v_mfma_f32_32x32x16_bf16 v[64:79], v[104:107], v[96:99], v[64:79]
	v_mov_b32_e32 v106, 0xf149f2ca
	v_mov_b32_e32 v107, 0xf149f2ca
	v_mov_b32_e32 v104, 0xf149f2ca
	v_mov_b32_e32 v105, 0xf149f2ca
	v_mov_b32_e32 v101, 0xf149f2ca
	v_mov_b32_e32 v98, 0xf149f2ca
	v_mov_b32_e32 v99, 0xf149f2ca
	v_mov_b32_e32 v96, 0xf149f2ca
	v_mov_b32_e32 v97, 0xf149f2ca
	s_and_saveexec_b64 s[18:19], s[14:15]
	v_readlane_b32 s27, v254, 25
	s_mov_b32 s30, 0x9000
	s_cbranch_execz .LBB0_298
; __device__ __forceinline__ void na_mask(f32x16& p0, f32x16& p1, int kr, int r0, int qrow, int qc, int c0, int hi, const float* bl) {
;     ...
;   } else {
;     const float* brow = bl + (kr - qrow + 7) * 31 + 15 - qc + 4 * hi;
;     const int d = 4 * hi - c0;
; #pragma unroll
;     for (int r = 0; r < 16; ++r) {
;       const int kc = (r & 3) + 8 * (r >> 2);
;       const float b0 = brow[kc], b1 = brow[kc + 32];
;       p0[r] = (unsigned)(d + kc) < 16u ? p0[r] + b0 : -1e30f; p1[r] = (unsigned)(d + kc + 32) < 16u ? p1[r] + b1 : -1e30f;
;     }
;   }
	v_sub_u32_e32 v96, s1, v189
	s_movk_i32 s1, 0x7c
	v_mul_lo_u32 v96, v96, s1
	v_add_u32_e32 v110, v184, v96
	ds_read_b32 v128, v110 offset:188
	v_mov_b32_e32 v96, 0xf149f2ca
	v_mov_b32_e32 v97, 0xf149f2ca
	v_mov_b32_e32 v98, 0xf149f2ca
	v_mov_b32_e32 v99, 0xf149f2ca
	v_mov_b32_e32 v100, 0xf149f2ca
	v_mov_b32_e32 v101, 0xf149f2ca
	v_mov_b32_e32 v102, 0xf149f2ca
	v_mov_b32_e32 v103, 0xf149f2ca
	v_mov_b32_e32 v104, 0xf149f2ca
	v_mov_b32_e32 v105, 0xf149f2ca
	v_mov_b32_e32 v106, 0xf149f2ca
	v_mov_b32_e32 v107, 0xf149f2ca
	v_mov_b32_e32 v108, 0xf149f2ca
	v_mov_b32_e32 v109, 0xf149f2ca
	v_mov_b32_e32 v115, 0xf149f2ca
	v_mov_b32_e32 v116, 0xf149f2ca
	ds_read_b32 v97, v110 offset:60
	ds_read_b32 v96, v110 offset:64
	ds_read_b32 v99, v110 offset:68
	ds_read_b32 v98, v110 offset:72
	ds_read_b32 v101, v110 offset:92
	ds_read_b32 v100, v110 offset:96
	ds_read_b32 v103, v110 offset:100
	ds_read_b32 v102, v110 offset:104
	ds_read_b32 v105, v110 offset:124
	ds_read_b32 v104, v110 offset:128
	ds_read_b32 v107, v110 offset:132
	ds_read_b32 v106, v110 offset:136
	ds_read_b32 v109, v110 offset:156
	ds_read_b32 v108, v110 offset:160
	ds_read_b32 v116, v110 offset:164
	ds_read_b32 v115, v110 offset:168
	s_waitcnt lgkmcnt(0)
	v_add_f32_e32 v97, v80, v97
	v_add_f32_e32 v96, v81, v96
	v_add_f32_e32 v99, v82, v99
	v_add_f32_e32 v98, v83, v98
	v_add_f32_e32 v101, v84, v101
	v_add_f32_e32 v100, v85, v100
	v_add_f32_e32 v103, v86, v103
	v_add_f32_e32 v102, v87, v102
	v_add_f32_e32 v105, v88, v105
	v_add_f32_e32 v104, v89, v104
	v_add_f32_e32 v107, v90, v107
	v_add_f32_e32 v106, v91, v106
	v_add_f32_e32 v109, v92, v109
	v_add_f32_e32 v108, v93, v108
	v_add_f32_e32 v116, v94, v116
	v_add_f32_e32 v115, v95, v115
	ds_read_b32 v80, v110 offset:192
	ds_read_b32 v81, v110 offset:196
	ds_read_b32 v82, v110 offset:200
	ds_read_b32 v83, v110 offset:220
	ds_read_b32 v84, v110 offset:224
	ds_read_b32 v85, v110 offset:228
	ds_read_b32 v86, v110 offset:232
	ds_read_b32 v87, v110 offset:252
	ds_read_b32 v88, v110 offset:256
	ds_read_b32 v89, v110 offset:260
	ds_read_b32 v90, v110 offset:264
	ds_read_b32 v91, v110 offset:284
	ds_read_b32 v92, v110 offset:288
	ds_read_b32 v111, v110 offset:292
	ds_read_b32 v93, v110 offset:296
	v_cndmask_b32_e64 v97, v239, v97, s[42:43]
	v_cndmask_b32_e64 v96, v239, v96, s[46:47]
	v_cndmask_b32_e64 v99, v239, v99, s[50:51]
	v_cndmask_b32_e64 v98, v239, v98, s[54:55]
	v_cndmask_b32_e64 v101, v239, v101, s[58:59]
	v_cndmask_b32_e64 v100, v239, v100, s[62:63]
	v_cndmask_b32_e64 v103, v239, v103, s[66:67]
	v_cndmask_b32_e64 v102, v239, v102, s[70:71]
	v_cndmask_b32_e64 v105, v239, v105, s[74:75]
	v_cndmask_b32_e64 v104, v239, v104, s[78:79]
	v_cndmask_b32_e64 v107, v239, v107, s[82:83]
	v_cndmask_b32_e64 v106, v239, v106, s[86:87]
	v_cndmask_b32_e64 v109, v239, v109, s[90:91]
	v_cndmask_b32_e64 v108, v239, v108, s[94:95]
	v_cndmask_b32_e64 v116, v239, v116, s[4:5]
	v_cndmask_b32_e64 v115, v239, v115, s[8:9]
	s_waitcnt lgkmcnt(14)
	v_add_f32_e32 v64, v64, v128
	s_waitcnt lgkmcnt(1)
	v_add_f32_e32 v78, v78, v111
	v_add_f32_e32 v77, v77, v92
	v_add_f32_e32 v76, v76, v91
	v_add_f32_e32 v75, v75, v90
	v_add_f32_e32 v74, v74, v89
	v_add_f32_e32 v73, v73, v88
	v_add_f32_e32 v72, v72, v87
	v_add_f32_e32 v71, v71, v86
	v_add_f32_e32 v70, v70, v85
	v_add_f32_e32 v69, v69, v84
	v_add_f32_e32 v68, v68, v83
	v_add_f32_e32 v67, v67, v82
	v_add_f32_e32 v66, v66, v81
	v_add_f32_e32 v65, v65, v80
	v_cndmask_b32_e64 v128, v239, v64, s[44:45]
	s_waitcnt lgkmcnt(0)
	v_add_f32_e32 v64, v79, v93
	v_cndmask_b32_e64 v110, v239, v78, s[6:7]
	v_cndmask_b32_e64 v111, v239, v77, s[96:97]
	v_cndmask_b32_e64 v114, v239, v76, s[92:93]
	v_cndmask_b32_e64 v117, v239, v75, s[88:89]
	v_cndmask_b32_e64 v118, v239, v74, s[84:85]
	v_cndmask_b32_e64 v119, v239, v73, s[80:81]
	v_cndmask_b32_e64 v120, v239, v72, s[76:77]
	v_cndmask_b32_e64 v121, v239, v71, s[72:73]
	v_cndmask_b32_e64 v122, v239, v70, s[68:69]
	v_cndmask_b32_e64 v123, v239, v69, s[64:65]
	v_cndmask_b32_e64 v124, v239, v68, s[60:61]
	v_cndmask_b32_e64 v125, v239, v67, s[56:57]
	v_cndmask_b32_e64 v126, v239, v66, s[52:53]
	v_cndmask_b32_e64 v127, v239, v65, s[48:49]
	v_cndmask_b32_e64 v129, v239, v64, s[10:11]
